# nt policy on the prep phase's read-once f32 weight/x loads and on the final f32 output stores
# speedup vs baseline: 1.0105x; 1.0105x over previous
; __device__ __forceinline__ void wtile_load(const WTile& w, int t, f32x4& a, f32x4& b, float& rsc) {
;     const int kk = t >> 3, ns = (t & 7) * 8; const int nd = w.n0 + ns; int nsrc = nd; bool valid = true; float cs = 1.0f;
;     if (w.mode == 0) { if (nd < 1536) nsrc = nd; else if (nd < 2048) nsrc = nd + 32; else if (nd < 2080) nsrc = nd - 512; else if (nd < 2304) valid = false; else nsrc = nd - 224; if (nd < 256) cs = 0.125f; }
;     a = (f32x4){0.f, 0.f, 0.f, 0.f}; b = a;
;     if (valid) { const float* sp = w.src + (size_t)(w.k0 + kk) * w.ldsrc + nsrc; a = *(const f32x4*)sp; b = *(const f32x4*)(sp + 4); }
;     rsc = (w.g ? w.g[w.k0 + kk] : 1.0f) * cs;
.LBB0_29:
	v_mov_b32_e32 v6, 0
	v_ashrrev_i32_e32 v15, 3, v1
	v_mov_b32_e32 v8, v6
	v_mov_b32_e32 v9, v6
	v_mov_b32_e32 v7, v6
	v_add_u32_e32 v4, s6, v15
	v_mov_b64_e32 v[12:13], v[8:9]
	v_ashrrev_i32_e32 v5, 31, v4
	v_mov_b64_e32 v[10:11], v[6:7]
	s_and_saveexec_b64 s[14:15], s[16:17]
	s_cbranch_execz .LBB0_31
	v_mul_lo_u32 v3, s18, v5
	v_mul_lo_u32 v8, s19, v4
	v_mad_u64_u32 v[6:7], s[16:17], s18, v4, 0
	v_add3_u32 v7, v7, v3, v8
	v_lshl_add_u64 v[6:7], v[6:7], 2, s[10:11]
	v_ashrrev_i32_e32 v3, 31, v2
	v_lshl_add_u64 v[2:3], v[2:3], 2, v[6:7]
	global_load_dwordx4 v[6:9], v[2:3], off offset:16 nt
	global_load_dwordx4 v[10:13], v[2:3], off nt

; __device__ __forceinline__ void wtile_load(const WTile& w, int t, f32x4& a, f32x4& b, float& rsc) {
;     const int kk = t >> 3, ns = (t & 7) * 8; const int nd = w.n0 + ns; int nsrc = nd; bool valid = true; float cs = 1.0f;
;     if (w.mode == 0) { if (nd < 1536) nsrc = nd; else if (nd < 2048) nsrc = nd + 32; else if (nd < 2080) nsrc = nd - 512; else if (nd < 2304) valid = false; else nsrc = nd - 224; if (nd < 256) cs = 0.125f; }
;     a = (f32x4){0.f, 0.f, 0.f, 0.f}; b = a;
;     if (valid) { const float* sp = w.src + (size_t)(w.k0 + kk) * w.ldsrc + nsrc; a = *(const f32x4*)sp; b = *(const f32x4*)(sp + 4); }
;     rsc = (w.g ? w.g[w.k0 + kk] : 1.0f) * cs;
.LBB0_64:
	v_mov_b32_e32 v4, v2
	v_mov_b32_e32 v5, v2
	v_mov_b32_e32 v3, v2
	v_add_u32_e32 v20, s52, v15
	v_mov_b64_e32 v[8:9], v[4:5]
	v_mov_b64_e32 v[12:13], v[4:5]
	v_ashrrev_i32_e32 v21, 31, v20
	v_mov_b64_e32 v[6:7], v[2:3]
	v_mov_b64_e32 v[10:11], v[2:3]
	s_and_saveexec_b64 s[18:19], s[22:23]
	s_cbranch_execz .LBB0_35
	v_mul_lo_u32 v3, s20, v21
	v_mul_lo_u32 v6, s21, v20
	v_mad_u64_u32 v[4:5], s[20:21], s20, v20, 0
	v_add3_u32 v5, v5, v3, v6
	v_lshl_add_u64 v[4:5], v[4:5], 2, s[14:15]
	v_ashrrev_i32_e32 v19, 31, v18
	v_lshl_add_u64 v[4:5], v[18:19], 2, v[4:5]
	global_load_dwordx4 v[6:9], v[4:5], off offset:16 nt
	global_load_dwordx4 v[10:13], v[4:5], off nt
	s_branch .LBB0_35

; __device__ __forceinline__ unsigned cvt_pk_bf16(float lo, float hi) { unsigned r; asm volatile("v_cvt_pk_bf16_f32 %0, %1, %2" : "=v"(r) : "v"(lo), "v"(hi)); return r; }
; PHASE_FN void phase_prep(const Params& p, float* ldsf) {
;     ...
;     { bf16_t* wsb = (bf16_t*)(ws + WS_WSB);
;       for (int i = (bx * 512 + tid) * 4; i < DEPTH * 4 * 128 * 128; i += G * 512 * 4) { const f32x4 v = *(const f32x4*)(p.w_s + i); u32x2 w; w.x = cvt_pk_bf16(v[0], v[1]); w.y = cvt_pk_bf16(v[2], v[3]); *(u32x2*)(wsb + i) = w; } }
.LBB0_70:
	v_add_u32_e32 v2, s6, v2
	global_load_dwordx4 v[8:11], v[4:5], off nt
	v_cmp_lt_i32_e32 vcc, s3, v2
	v_lshl_add_u64 v[4:5], v[4:5], 0, s[10:11]
	s_or_b64 s[14:15], vcc, s[14:15]
	s_waitcnt vmcnt(0)
	v_cvt_pk_bf16_f32 v8, v8, v9
	v_cvt_pk_bf16_f32 v9, v10, v11
	global_store_dwordx2 v[6:7], v[8:9], off
	v_lshl_add_u64 v[6:7], v[6:7], 0, s[12:13]
	s_andn2_b64 exec, exec, s[14:15]
	s_cbranch_execnz .LBB0_70

; __device__ __forceinline__ unsigned cvt_pk_bf16(float lo, float hi) { unsigned r; asm volatile("v_cvt_pk_bf16_f32 %0, %1, %2" : "=v"(r) : "v"(lo), "v"(hi)); return r; }
; PHASE_FN void phase_prep(const Params& p, float* ldsf) {
;     ...
;     { bf16_t* xb = (bf16_t*)(ws + WS_XB); float* ssq = (float*)(ws + WS_SSQ); const int wid = tid >> 6, lane = tid & 63;
;       for (int r = bx * 8 + wid; r < T; r += G * 8) { const float* xr = p.x + (size_t)r * D; float ss = 0.f;
; #pragma unroll
;           for (int i = 0; i < 4; ++i) { const int c = i * 256 + lane * 4; const f32x4 v = *(const f32x4*)(xr + c); ss += (v[0] * v[0] + v[1] * v[1]) + (v[2] * v[2] + v[3] * v[3]);
;               u32x2 w; w.x = cvt_pk_bf16(v[0], v[1]); w.y = cvt_pk_bf16(v[2], v[3]); *(u32x2*)(xb + (size_t)r * D + c) = w; }
; #pragma unroll
;           for (int o = 32; o >= 1; o >>= 1) ss += __shfl_xor(ss, o);
;           if (lane < 16) ssq[(size_t)r * 16 + lane] = lane == 0 ? ss : 0.f; } }
.LBB0_74:
	s_waitcnt lgkmcnt(0)
	global_load_dwordx4 v[18:21], v[4:5], off offset:-2048 nt
	s_waitcnt vmcnt(0)
	v_cvt_pk_bf16_f32 v22, v18, v19
	v_cvt_pk_bf16_f32 v23, v20, v21
	global_store_dwordx2 v[6:7], v[22:23], off offset:-1024
	global_load_dwordx4 v[22:25], v[4:5], off offset:-1024 nt
	s_waitcnt vmcnt(0)
	v_cvt_pk_bf16_f32 v26, v22, v23
	v_cvt_pk_bf16_f32 v27, v24, v25
	global_store_dwordx2 v[6:7], v[26:27], off offset:-512
	global_load_dwordx4 v[26:29], v[4:5], off nt
	s_waitcnt vmcnt(0)
	v_cvt_pk_bf16_f32 v30, v26, v27
	v_cvt_pk_bf16_f32 v31, v28, v29
	global_store_dwordx2 v[6:7], v[30:31], off
	global_load_dwordx4 v[30:33], v[4:5], off offset:1024 nt
	v_cmp_lt_i32_e64 s[6:7], v11, v10
	v_mul_f32_e32 v19, v19, v19
	v_mul_f32_e32 v21, v21, v21
	v_fmac_f32_e32 v19, v18, v18
	v_fmac_f32_e32 v21, v20, v20
	v_add_f32_e32 v18, v19, v21
	v_mul_f32_e32 v19, v23, v23
	v_mul_f32_e32 v20, v25, v25
	v_fmac_f32_e32 v19, v22, v22
	v_fmac_f32_e32 v20, v24, v24
	v_add_f32_e32 v19, v19, v20
	v_add_f32_e32 v18, v18, v19
	v_mul_f32_e32 v19, v27, v27
	v_mul_f32_e32 v20, v29, v29
	v_fmac_f32_e32 v19, v26, v26
	v_fmac_f32_e32 v20, v28, v28
	v_add_f32_e32 v19, v19, v20
	v_add_f32_e32 v18, v18, v19
	s_waitcnt vmcnt(0)
	v_mul_f32_e32 v19, v31, v31
	v_mul_f32_e32 v20, v33, v33
	v_fmac_f32_e32 v19, v30, v30
	v_fmac_f32_e32 v20, v32, v32
	v_cndmask_b32_e64 v17, v1, v11, s[6:7]
	v_add_f32_e32 v19, v19, v20
	v_lshlrev_b32_e32 v17, 2, v17
	v_add_f32_e32 v18, v18, v19
	ds_bpermute_b32 v17, v17, v18
	v_cmp_lt_i32_e64 s[6:7], v12, v10
	v_cvt_pk_bf16_f32 v20, v30, v31
	v_cvt_pk_bf16_f32 v21, v32, v33
	global_store_dwordx2 v[6:7], v[20:21], off offset:512
	s_waitcnt lgkmcnt(0)
	v_add_f32_e32 v17, v18, v17
	v_cndmask_b32_e64 v19, v1, v12, s[6:7]
	v_lshlrev_b32_e32 v19, 2, v19
	ds_bpermute_b32 v18, v19, v17
	v_cmp_lt_i32_e64 s[6:7], v13, v10
	s_waitcnt lgkmcnt(0)
	v_add_f32_e32 v17, v17, v18
	v_cndmask_b32_e64 v19, v1, v13, s[6:7]
	v_lshlrev_b32_e32 v19, 2, v19
	ds_bpermute_b32 v18, v19, v17
	v_cmp_lt_i32_e64 s[6:7], v14, v10
	s_waitcnt lgkmcnt(0)
	v_add_f32_e32 v17, v17, v18
	v_cndmask_b32_e64 v19, v1, v14, s[6:7]
	v_lshlrev_b32_e32 v19, 2, v19
	ds_bpermute_b32 v18, v19, v17
	v_cmp_lt_i32_e64 s[6:7], v15, v10
	s_waitcnt lgkmcnt(0)
	v_add_f32_e32 v17, v17, v18
	v_cndmask_b32_e64 v19, v1, v15, s[6:7]
	v_lshlrev_b32_e32 v19, 2, v19
	ds_bpermute_b32 v18, v19, v17
	v_cmp_lt_i32_e64 s[6:7], v16, v10
	s_waitcnt lgkmcnt(0)
	v_add_f32_e32 v17, v17, v18
	v_cndmask_b32_e64 v19, v1, v16, s[6:7]
	v_lshlrev_b32_e32 v18, 2, v19
	ds_bpermute_b32 v18, v18, v17
	s_and_saveexec_b64 s[6:7], vcc
	s_cbranch_execz .LBB0_73
	s_waitcnt lgkmcnt(0)
	v_add_f32_e32 v17, v17, v18
	v_cndmask_b32_e64 v17, 0, v17, s[4:5]
	global_store_dword v[2:3], v17, off
	s_branch .LBB0_73

; __device__ __forceinline__ float bflo(unsigned w) { return __uint_as_float(w << 16); }
; __device__ __forceinline__ float bfhi(unsigned w) { return __uint_as_float(w & 0xffff0000u); }
; __global__ void __launch_bounds__(512, 2) fwd_megakernel(Params p) {
;     ...
;     { const int tid = threadIdx.x;
;       for (size_t i = ((size_t)bx * 512 + tid) * 8; i < (size_t)T * D; i += (size_t)G * 512 * 8) {
;           const int r = (int)(i >> 10), c = (int)(i & 1023);
;           const float* sp = SSQ + (size_t)r * 16; float s = 0.f;
; #pragma unroll
;           for (int j = 0; j < 4; ++j) { const f32x4 q = *(const f32x4*)(sp + 4 * j); s += (q[0] + q[1]) + (q[2] + q[3]); }
;           const float rs = rsqrtf(s * (1.0f / 1024.0f) + EPS);
;           const u32x4 w = *(const u32x4*)(XB + i); const f32x4 g0 = *(const f32x4*)(p.final_norm_g + c), g1 = *(const f32x4*)(p.final_norm_g + c + 4);
;           *(f32x4*)(p.out + i) = (f32x4){bflo(w.x), bfhi(w.x), bflo(w.y), bfhi(w.y)} * rs * g0;
;           *(f32x4*)(p.out + i + 4) = (f32x4){bflo(w.z), bfhi(w.z), bflo(w.w), bfhi(w.w)} * rs * g1; } }
.LBB0_692:
	v_lshrrev_b32_e32 v7, 4, v0
	v_and_b32_e32 v7, 0x3fffc0, v7
	global_load_dwordx4 v[8:11], v7, s[12:13] offset:48
	global_load_dwordx4 v[12:15], v7, s[12:13] offset:32
	global_load_dwordx4 v[16:19], v7, s[12:13] offset:16
	global_load_dwordx4 v[20:23], v7, s[12:13]
	global_load_dwordx4 v[24:27], v[2:3], off
	v_and_b32_e32 v7, 0x3f8, v0
	v_lshlrev_b32_e32 v7, 2, v7
	global_load_dwordx4 v[28:31], v7, s[14:15]
	global_load_dwordx4 v[32:35], v7, s[14:15] offset:16
	v_lshl_add_u64 v[0:1], v[0:1], 0, s[0:1]
	v_cmp_lt_u64_e32 vcc, s[8:9], v[0:1]
	s_or_b64 s[6:7], vcc, s[6:7]
	v_lshl_add_u64 v[2:3], v[2:3], 0, s[4:5]
	s_waitcnt vmcnt(5)
	v_add_f32_e32 v12, v12, v13
	v_add_f32_e32 v14, v14, v15
	s_waitcnt vmcnt(3)
	v_mov_b32_e32 v40, v21
	v_mov_b32_e32 v41, v22
	v_mov_b32_e32 v21, v23
	v_mov_b32_e32 v22, v17
	v_mov_b32_e32 v23, v18
	v_mov_b32_e32 v17, v19
	v_mov_b32_e32 v13, v10
	v_mov_b32_e32 v15, v11
	v_pk_add_f32 v[10:11], v[40:41], v[20:21]
	v_pk_add_f32 v[16:17], v[22:23], v[16:17]
	v_add_f32_e32 v7, v10, v11
	v_pk_add_f32 v[10:11], v[16:17], v[16:17] op_sel:[0,1] op_sel_hi:[1,0]
	v_mov_b32_e32 v19, v8
	v_add_f32_e32 v18, 0, v7
	v_mov_b32_e32 v11, v9
	v_pk_add_f32 v[12:13], v[12:13], v[14:15]
	v_pk_add_f32 v[8:9], v[18:19], v[10:11]
	s_waitcnt vmcnt(2)
	v_lshlrev_b32_e32 v36, 16, v24
	v_pk_add_f32 v[8:9], v[8:9], v[12:13]
	v_and_b32_e32 v37, 0xffff0000, v24
	v_add_f32_e32 v7, v8, v9
	v_fmamk_f32 v7, v7, 0x3a800000, v6
	v_mul_f32_e32 v8, 0x4b800000, v7
	v_cmp_gt_f32_e32 vcc, s10, v7
	v_lshlrev_b32_e32 v24, 16, v25
	v_and_b32_e32 v25, 0xffff0000, v25
	v_cndmask_b32_e32 v7, v7, v8, vcc
	v_rsq_f32_e32 v7, v7
	v_lshlrev_b32_e32 v38, 16, v26
	v_and_b32_e32 v39, 0xffff0000, v26
	v_lshlrev_b32_e32 v26, 16, v27
	v_mul_f32_e32 v8, 0x45800000, v7
	v_cndmask_b32_e32 v8, v7, v8, vcc
	v_and_b32_e32 v27, 0xffff0000, v27
	v_pk_mul_f32 v[12:13], v[8:9], v[36:37] op_sel_hi:[0,1]
	v_pk_mul_f32 v[10:11], v[8:9], v[24:25] op_sel_hi:[0,1]
	v_pk_mul_f32 v[16:17], v[8:9], v[38:39] op_sel_hi:[0,1]
	v_pk_mul_f32 v[14:15], v[8:9], v[26:27] op_sel_hi:[0,1]
	s_waitcnt vmcnt(1)
	v_pk_mul_f32 v[10:11], v[30:31], v[10:11]
	v_pk_mul_f32 v[8:9], v[28:29], v[12:13]
	s_waitcnt vmcnt(0)
	v_pk_mul_f32 v[14:15], v[34:35], v[14:15]
	v_pk_mul_f32 v[12:13], v[32:33], v[16:17]
	global_store_dwordx4 v[4:5], v[8:11], off offset:-16 nt
	global_store_dwordx4 v[4:5], v[12:15], off nt
	v_lshl_add_u64 v[4:5], v[4:5], 0, s[2:3]
	s_andn2_b64 exec, exec, s[6:7]
	s_cbranch_execnz .LBB0_692
